# band attention prompt loop: V-fragment ds_read_b64_tr reads issued behind the QK MFMA chain in place of s_nop 10 (MFMA-shadow LDS interleave), on top of sw3
# speedup vs baseline: 1.0070x; 1.0036x over previous
; template <int D>
; __device__ __forceinline__ void band_unit(LAS unsigned char* lds, const bf16_t* Kg, const bf16_t* Vg, const int ntile, const bf16_t* Qg, bf16_t* Og, float* ssa, const int nci, const int crel0, const LAS float* tb) {
;     ...
;             for (int s8 = 0; s8 < 8; ++s8) kf[s8] = *(const LAS bf16x8*)(st + koff[s8]);
;             asm volatile("s_waitcnt lgkmcnt(0)" : "+v"(kf[0]), "+v"(kf[1]), "+v"(kf[2]), "+v"(kf[3]), "+v"(kf[4]), "+v"(kf[5]), "+v"(kf[6]), "+v"(kf[7]) :: "memory");
;             __builtin_amdgcn_s_setprio(1);
; #pragma unroll
;             for (int s8 = 0; s8 < 8; ++s8) sc = __builtin_amdgcn_mfma_f32_32x32x16_bf16(kf[s8], qf[s8], sc, 0, 0, 0);
;             __builtin_amdgcn_s_setprio(0);
;             s16x4 va[8], vb[8];
;             { const unsigned sb = (unsigned)(size_t)st; VTR8(va, sb + voff[0][0], sb + voff[1][0], sb + voff[0][1], sb + voff[1][1]); VTR8(vb, sb + voff[0][2], sb + voff[1][2], sb + voff[0][3], sb + voff[1][3]); }
;             float pe[16];
; #pragma unroll
;             for (int r = 0; r < 16; ++r) { pe[r] = __builtin_amdgcn_exp2f(sc[r]); lsum += pe[r]; }
;             u32x4 pw0, pw1;
;             pw0.x = cvtpk(pe[0], pe[1]); pw0.y = cvtpk(pe[2], pe[3]); pw0.z = cvtpk(pe[4], pe[5]); pw0.w = cvtpk(pe[6], pe[7]);
;             pw1.x = cvtpk(pe[8], pe[9]); pw1.y = cvtpk(pe[10], pe[11]); pw1.z = cvtpk(pe[12], pe[13]); pw1.w = cvtpk(pe[14], pe[15]);
;             VTRW(8, va, pw0, pw1);
;             const bf16x8 pa0 = __builtin_bit_cast(bf16x8, pw0), pa1 = __builtin_bit_cast(bf16x8, pw1);
;             o[0] = __builtin_amdgcn_mfma_f32_32x32x16_bf16(pa0, VFR2(va[0], va[1]), o[0], 0, 0, 0); o[0] = __builtin_amdgcn_mfma_f32_32x32x16_bf16(pa1, VFR2(va[2], va[3]), o[0], 0, 0, 0);
;             o[1] = __builtin_amdgcn_mfma_f32_32x32x16_bf16(pa0, VFR2(va[4], va[5]), o[1], 0, 0, 0); o[1] = __builtin_amdgcn_mfma_f32_32x32x16_bf16(pa1, VFR2(va[6], va[7]), o[1], 0, 0, 0);
;             VTRW(0, vb, pw0, pw1);
;             o[2] = __builtin_amdgcn_mfma_f32_32x32x16_bf16(pa0, VFR2(vb[0], vb[1]), o[2], 0, 0, 0); o[2] = __builtin_amdgcn_mfma_f32_32x32x16_bf16(pa1, VFR2(vb[2], vb[3]), o[2], 0, 0, 0);
;             o[3] = __builtin_amdgcn_mfma_f32_32x32x16_bf16(pa0, VFR2(vb[4], vb[5]), o[3], 0, 0, 0); o[3] = __builtin_amdgcn_mfma_f32_32x32x16_bf16(pa1, VFR2(vb[6], vb[7]), o[3], 0, 0, 0);
.LBB0_594:
	s_add_i32 s66, s14, 0xfffe4000
	s_and_b32 s66, s66, 0x1c000
	s_add_i32 s66, s66, 0
	v_add3_u32 v170, s66, v147, v142
	v_add3_u32 v126, s66, v148, v142
	v_add3_u32 v122, s66, v149, v142
	v_add3_u32 v116, s66, v150, v142
	v_add3_u32 v133, s66, v143, v142
	v_add3_u32 v134, s66, v144, v142
	v_add3_u32 v135, s66, v145, v142
	v_add3_u32 v169, s66, v146, v142
	ds_read_b128 v[116:119], v116
	ds_read_b128 v[122:125], v122
	ds_read_b128 v[126:129], v126
	ds_read_b128 v[170:173], v170
	ds_read_b128 v[180:183], v169
	ds_read_b128 v[184:187], v135
	ds_read_b128 v[188:191], v134
	ds_read_b128 v[192:195], v133
	s_waitcnt lgkmcnt(0)
	s_waitcnt lgkmcnt(0)
	s_setprio 1
	v_mfma_f32_32x32x16_bf16 v[68:83], v[192:195], v[84:87], v[68:83]
	v_mfma_f32_32x32x16_bf16 v[68:83], v[188:191], v[88:91], v[68:83]
	v_mfma_f32_32x32x16_bf16 v[68:83], v[184:187], v[92:95], v[68:83]
	v_mfma_f32_32x32x16_bf16 v[68:83], v[180:183], v[96:99], v[68:83]
	v_mfma_f32_32x32x16_bf16 v[68:83], v[170:173], v[100:103], v[68:83]
	v_mfma_f32_32x32x16_bf16 v[68:83], v[126:129], v[104:107], v[68:83]
	v_mfma_f32_32x32x16_bf16 v[68:83], v[122:125], v[108:111], v[68:83]
	v_mfma_f32_32x32x16_bf16 v[68:83], v[116:119], v[112:115], v[68:83]
	s_setprio 0
	v_add_u32_e32 v116, s66, v152
	v_add_u32_e32 v117, s66, v156
	v_add_u32_e32 v118, s66, v153
	v_add_u32_e32 v119, s66, v157
	ds_read_b64_tr_b16 v[180:181], v116
	ds_read_b64_tr_b16 v[182:183], v117
	ds_read_b64_tr_b16 v[170:171], v116 offset:4096
	ds_read_b64_tr_b16 v[172:173], v117 offset:4096
	ds_read_b64_tr_b16 v[126:127], v118
	ds_read_b64_tr_b16 v[128:129], v119
	ds_read_b64_tr_b16 v[122:123], v118 offset:4096
	ds_read_b64_tr_b16 v[124:125], v119 offset:4096
	v_add_u32_e32 v133, s66, v154
	v_add_u32_e32 v134, s66, v158
	v_add_u32_e32 v135, s66, v155
	v_add_u32_e32 v169, s66, v159
	ds_read_b64_tr_b16 v[192:193], v133
	ds_read_b64_tr_b16 v[194:195], v134
	ds_read_b64_tr_b16 v[188:189], v133 offset:4096
	ds_read_b64_tr_b16 v[190:191], v134 offset:4096
	ds_read_b64_tr_b16 v[184:185], v135
	ds_read_b64_tr_b16 v[186:187], v169
	ds_read_b64_tr_b16 v[116:117], v135 offset:4096
	ds_read_b64_tr_b16 v[118:119], v169 offset:4096
	v_exp_f32_e32 v68, v68
	v_exp_f32_e32 v69, v69
	v_exp_f32_e32 v70, v70
	v_exp_f32_e32 v71, v71
	v_add_f32_e32 v0, v0, v68
	v_exp_f32_e32 v72, v72
	v_add_f32_e32 v0, v69, v0
	v_exp_f32_e32 v73, v73
	v_add_f32_e32 v0, v70, v0
	v_exp_f32_e32 v74, v74
	v_add_f32_e32 v0, v71, v0
	v_exp_f32_e32 v75, v75
	v_add_f32_e32 v0, v72, v0
	v_exp_f32_e32 v76, v76
	v_add_f32_e32 v0, v73, v0
	v_exp_f32_e32 v77, v77
	v_add_f32_e32 v0, v74, v0
	v_exp_f32_e32 v78, v78
	v_add_f32_e32 v0, v75, v0
	v_exp_f32_e32 v79, v79
	v_add_f32_e32 v0, v76, v0
	v_exp_f32_e32 v80, v80
	v_add_f32_e32 v0, v77, v0
	v_exp_f32_e32 v81, v81
	v_add_f32_e32 v0, v78, v0
	v_exp_f32_e32 v82, v82
	v_exp_f32_e32 v83, v83
	v_add_f32_e32 v0, v79, v0
	v_add_f32_e32 v0, v80, v0
	v_add_f32_e32 v0, v81, v0
	v_add_f32_e32 v0, v82, v0
	v_cvt_pk_bf16_f32 v68, v68, v69
	v_cvt_pk_bf16_f32 v69, v70, v71
	v_cvt_pk_bf16_f32 v70, v72, v73
	v_cvt_pk_bf16_f32 v71, v74, v75
	v_cvt_pk_bf16_f32 v72, v76, v77
	v_cvt_pk_bf16_f32 v73, v78, v79
	v_cvt_pk_bf16_f32 v74, v80, v81
	v_cvt_pk_bf16_f32 v75, v82, v83
	v_add_f32_e32 v0, v83, v0
	s_waitcnt lgkmcnt(8)
	s_nop 0
	v_mov_b64_e32 v[78:79], v[74:75]
	v_mov_b64_e32 v[82:83], v[70:71]
	v_mov_b64_e32 v[76:77], v[72:73]
	v_mov_b64_e32 v[80:81], v[68:69]
	v_mfma_f32_32x32x16_bf16 v[34:49], v[68:71], v[180:183], v[34:49]
	s_waitcnt lgkmcnt(0)
	v_mfma_f32_32x32x16_bf16 v[50:65], v[68:71], v[126:129], v[50:65]
	v_mfma_f32_32x32x16_bf16 v[18:33], v[68:71], v[192:195], v[18:33]
	v_mfma_f32_32x32x16_bf16 v[2:17], v[68:71], v[184:187], v[2:17]
	v_mfma_f32_32x32x16_bf16 v[34:49], v[72:75], v[170:173], v[34:49]
	v_mfma_f32_32x32x16_bf16 v[50:65], v[72:75], v[122:125], v[50:65]
	v_mfma_f32_32x32x16_bf16 v[18:33], v[72:75], v[188:191], v[18:33]
	v_mfma_f32_32x32x16_bf16 v[2:17], v[72:75], v[116:119], v[2:17]
